# GEMM loops: first K-iteration peeled with SrcC=0, accumulator zeroing (128 v_mov per tile) removed
# speedup vs baseline: 1.0038x; 1.0033x over previous
.LBB0_191:
	s_ashr_i32 s23, s22, 31
	s_lshl_b64 s[8:9], s[22:23], 20
	s_add_u32 s24, s14, s8
	s_addc_u32 s25, s15, s9
	s_and_b64 s[8:9], s[38:39], exec
	s_cselect_b32 s8, s25, s35
	s_cselect_b32 s9, s24, s34
	s_ashr_i32 s63, s62, 31
	s_lshl_b64 s[16:17], s[62:63], 20
	s_add_u32 s26, s52, s16
	s_addc_u32 s27, s53, s17
	s_and_b64 s[16:17], s[38:39], exec
	s_cselect_b32 s16, s27, s5
	s_cselect_b32 s17, s26, s4
	s_add_u32 s23, s4, 0x100
	s_addc_u32 s31, s5, 0
	s_add_u32 s34, s34, 0x80080
	v_mov_b32_e32 v0, 0
	s_addc_u32 s35, s35, 0
	s_mov_b32 s40, -2
	s_add_u32 s4, s34, 0xfff80080
	s_addc_u32 s5, s35, -1
	s_add_i32 s41, 0, 0x10000
	s_cmp_eq_u32 s40, 28
	s_cselect_b32 s37, s8, s5
	s_cselect_b32 s36, s9, s4
	v_add_u32_e32 v8, s41, v190
	s_cselect_b32 s5, s16, s31
	s_cselect_b32 s4, s17, s23
	s_add_i32 s48, 0, 0x14000
	ds_read_b128 v[142:145], v8
	ds_read_b128 v[146:149], v8 offset:1024
	ds_read_b128 v[150:153], v8 offset:2048
	ds_read_b128 v[172:175], v8 offset:3072
	v_add_u32_e32 v8, s48, v190
	ds_read_b128 v[176:179], v8
	ds_read_b128 v[202:205], v8 offset:1024
	ds_read_b128 v[206:209], v8 offset:2048
	ds_read_b128 v[210:213], v8 offset:3072
	v_lshl_add_u64 v[180:181], s[34:35], 0, v[140:141]
	s_add_i32 m0, s29, 0xc000
	ds_read_b128 v[214:217], v200
	ds_read_b128 v[218:221], v200 offset:1024
	ds_read_b128 v[226:229], v200 offset:2048
	ds_read_b128 v[230:233], v200 offset:3072
	ds_read_b128 v[234:237], v200 offset:4096
	ds_read_b128 v[238:241], v200 offset:5120
	ds_read_b128 v[242:245], v200 offset:6144
	ds_read_b128 v[246:249], v200 offset:7168
	global_load_lds_dwordx4 v[180:181], off
	v_lshl_add_u64 v[180:181], s[34:35], 0, v[138:139]
	s_add_i32 m0, s29, 0xe000
	s_nop 0
	global_load_lds_dwordx4 v[180:181], off
	s_waitcnt vmcnt(8)
	s_waitcnt lgkmcnt(0)
	s_barrier
	s_setprio 1
	s_waitcnt lgkmcnt(0)
	v_mfma_f32_16x16x32_bf16 v[126:129], v[142:145], v[214:217], 0
	v_mfma_f32_16x16x32_bf16 v[118:121], v[150:153], v[214:217], 0
	v_mfma_f32_16x16x32_bf16 v[110:113], v[142:145], v[226:229], 0
	v_mfma_f32_16x16x32_bf16 v[102:105], v[150:153], v[226:229], 0
	v_mfma_f32_16x16x32_bf16 v[94:97], v[142:145], v[234:237], 0
	v_mfma_f32_16x16x32_bf16 v[86:89], v[150:153], v[234:237], 0
	v_mfma_f32_16x16x32_bf16 v[78:81], v[142:145], v[242:245], 0
	v_mfma_f32_16x16x32_bf16 v[70:73], v[150:153], v[242:245], 0
	v_mfma_f32_16x16x32_bf16 v[126:129], v[146:149], v[218:221], v[126:129]
	v_mfma_f32_16x16x32_bf16 v[118:121], v[172:175], v[218:221], v[118:121]
	v_mfma_f32_16x16x32_bf16 v[110:113], v[146:149], v[230:233], v[110:113]
	v_mfma_f32_16x16x32_bf16 v[102:105], v[172:175], v[230:233], v[102:105]
	v_mfma_f32_16x16x32_bf16 v[94:97], v[146:149], v[238:241], v[94:97]
	v_mfma_f32_16x16x32_bf16 v[86:89], v[172:175], v[238:241], v[86:89]
	v_mfma_f32_16x16x32_bf16 v[78:81], v[146:149], v[246:249], v[78:81]
	v_mfma_f32_16x16x32_bf16 v[70:73], v[172:175], v[246:249], v[70:73]
	s_setprio 0
	s_setprio 1
	v_mfma_f32_16x16x32_bf16 v[122:125], v[176:179], v[214:217], 0
	v_mfma_f32_16x16x32_bf16 v[114:117], v[206:209], v[214:217], 0
	v_mfma_f32_16x16x32_bf16 v[106:109], v[176:179], v[226:229], 0
	v_mfma_f32_16x16x32_bf16 v[98:101], v[206:209], v[226:229], 0
	v_mfma_f32_16x16x32_bf16 v[90:93], v[176:179], v[234:237], 0
	v_mfma_f32_16x16x32_bf16 v[82:85], v[206:209], v[234:237], 0
	v_mfma_f32_16x16x32_bf16 v[74:77], v[176:179], v[242:245], 0
	v_mfma_f32_16x16x32_bf16 v[66:69], v[206:209], v[242:245], 0
	v_mfma_f32_16x16x32_bf16 v[122:125], v[202:205], v[218:221], v[122:125]
	v_mfma_f32_16x16x32_bf16 v[114:117], v[210:213], v[218:221], v[114:117]
	v_mfma_f32_16x16x32_bf16 v[106:109], v[202:205], v[230:233], v[106:109]
	v_mfma_f32_16x16x32_bf16 v[98:101], v[210:213], v[230:233], v[98:101]
	v_mfma_f32_16x16x32_bf16 v[90:93], v[202:205], v[238:241], v[90:93]
	v_mfma_f32_16x16x32_bf16 v[82:85], v[210:213], v[238:241], v[82:85]
	v_mfma_f32_16x16x32_bf16 v[74:77], v[202:205], v[246:249], v[74:77]
	v_mfma_f32_16x16x32_bf16 v[66:69], v[210:213], v[246:249], v[66:69]
	s_setprio 0
	s_barrier
	s_add_i32 s41, s41, s68
	v_lshl_add_u64 v[180:181], s[4:5], 0, v[132:133]
	s_mov_b32 m0, s41
	ds_read_b128 v[214:217], v200 offset:16384
	ds_read_b128 v[218:221], v200 offset:17408
	ds_read_b128 v[226:229], v200 offset:18432
	ds_read_b128 v[230:233], v200 offset:19456
	ds_read_b128 v[234:237], v200 offset:20480
	ds_read_b128 v[238:241], v200 offset:21504
	ds_read_b128 v[242:245], v200 offset:22528
	ds_read_b128 v[246:249], v200 offset:23552
	global_load_lds_dwordx4 v[180:181], off
	s_add_i32 m0, s41, 0x2000
	s_add_u32 s42, s4, 0x80000
	v_lshl_add_u64 v[222:223], s[4:5], 0, v[136:137]
	s_addc_u32 s43, s5, 0
	s_add_i32 s41, s48, s68
	global_load_lds_dwordx4 v[222:223], off
	v_lshl_add_u64 v[250:251], s[42:43], 0, v[132:133]
	s_mov_b32 m0, s41
	v_lshl_add_u64 v[154:155], s[36:37], 0, v[134:135]
	global_load_lds_dwordx4 v[250:251], off
	v_lshl_add_u64 v[250:251], s[42:43], 0, v[136:137]
	s_add_i32 m0, s41, 0x2000
	s_nop 0
	global_load_lds_dwordx4 v[250:251], off
	v_lshl_add_u64 v[250:251], s[36:37], 0, v[130:131]
	s_mov_b32 m0, s29
	s_nop 0
	global_load_lds_dwordx4 v[250:251], off
	s_mov_b32 m0, s56
	s_nop 0
	global_load_lds_dwordx4 v[154:155], off
	s_waitcnt vmcnt(8)
	s_waitcnt lgkmcnt(0)
	s_barrier
	s_setprio 1
	s_waitcnt lgkmcnt(0)
	v_mfma_f32_16x16x32_bf16 v[62:65], v[142:145], v[214:217], 0
	v_mfma_f32_16x16x32_bf16 v[54:57], v[150:153], v[214:217], 0
	v_mfma_f32_16x16x32_bf16 v[46:49], v[142:145], v[226:229], 0
	v_mfma_f32_16x16x32_bf16 v[38:41], v[150:153], v[226:229], 0
	v_mfma_f32_16x16x32_bf16 v[30:33], v[142:145], v[234:237], 0
	v_mfma_f32_16x16x32_bf16 v[22:25], v[150:153], v[234:237], 0
	v_mfma_f32_16x16x32_bf16 v[14:17], v[142:145], v[242:245], 0
	v_mfma_f32_16x16x32_bf16 v[4:7], v[150:153], v[242:245], 0
	v_mfma_f32_16x16x32_bf16 v[62:65], v[146:149], v[218:221], v[62:65]
	v_mfma_f32_16x16x32_bf16 v[54:57], v[172:175], v[218:221], v[54:57]
	v_mfma_f32_16x16x32_bf16 v[46:49], v[146:149], v[230:233], v[46:49]
	v_mfma_f32_16x16x32_bf16 v[38:41], v[172:175], v[230:233], v[38:41]
	v_mfma_f32_16x16x32_bf16 v[30:33], v[146:149], v[238:241], v[30:33]
	v_mfma_f32_16x16x32_bf16 v[22:25], v[172:175], v[238:241], v[22:25]
	v_mfma_f32_16x16x32_bf16 v[14:17], v[146:149], v[246:249], v[14:17]
	v_mfma_f32_16x16x32_bf16 v[4:7], v[172:175], v[246:249], v[4:7]
	s_setprio 0
	s_setprio 1
	v_mfma_f32_16x16x32_bf16 v[58:61], v[176:179], v[214:217], 0
	v_mfma_f32_16x16x32_bf16 v[50:53], v[206:209], v[214:217], 0
	v_mfma_f32_16x16x32_bf16 v[42:45], v[176:179], v[226:229], 0
	v_mfma_f32_16x16x32_bf16 v[34:37], v[206:209], v[226:229], 0
	v_mfma_f32_16x16x32_bf16 v[26:29], v[176:179], v[234:237], 0
	v_mfma_f32_16x16x32_bf16 v[18:21], v[206:209], v[234:237], 0
	v_mfma_f32_16x16x32_bf16 v[10:13], v[176:179], v[242:245], 0
	v_mfma_f32_16x16x32_bf16 v[0:3], v[206:209], v[242:245], 0
	v_mfma_f32_16x16x32_bf16 v[58:61], v[202:205], v[218:221], v[58:61]
	v_mfma_f32_16x16x32_bf16 v[50:53], v[210:213], v[218:221], v[50:53]
	v_mfma_f32_16x16x32_bf16 v[42:45], v[202:205], v[230:233], v[42:45]
	v_mfma_f32_16x16x32_bf16 v[34:37], v[210:213], v[230:233], v[34:37]
	v_mfma_f32_16x16x32_bf16 v[26:29], v[202:205], v[238:241], v[26:29]
	v_mfma_f32_16x16x32_bf16 v[18:21], v[210:213], v[238:241], v[18:21]
	v_mfma_f32_16x16x32_bf16 v[10:13], v[202:205], v[246:249], v[10:13]
	v_mfma_f32_16x16x32_bf16 v[0:3], v[210:213], v[246:249], v[0:3]
	s_setprio 0
	s_barrier
	s_add_i32 s41, 0, 0x18000
	v_add_u32_e32 v8, s41, v190
	s_add_i32 s42, 0, 0x1c000
	ds_read_b128 v[142:145], v8
	ds_read_b128 v[146:149], v8 offset:1024
	ds_read_b128 v[150:153], v8 offset:2048
	ds_read_b128 v[172:175], v8 offset:3072
	v_add_u32_e32 v8, s42, v190
	ds_read_b128 v[176:179], v8
	ds_read_b128 v[202:205], v8 offset:1024
	ds_read_b128 v[206:209], v8 offset:2048
	ds_read_b128 v[210:213], v8 offset:3072
	s_add_u32 s36, s36, 0x80000
	s_addc_u32 s37, s37, 0
	s_mov_b32 m0, s57
	v_lshl_add_u64 v[156:157], s[36:37], 0, v[130:131]
	ds_read_b128 v[214:217], v200 offset:32768
	ds_read_b128 v[218:221], v200 offset:33792
	ds_read_b128 v[226:229], v200 offset:34816
	ds_read_b128 v[230:233], v200 offset:35840
	ds_read_b128 v[234:237], v200 offset:36864
	ds_read_b128 v[238:241], v200 offset:37888
	ds_read_b128 v[242:245], v200 offset:38912
	ds_read_b128 v[246:249], v200 offset:39936
	global_load_lds_dwordx4 v[156:157], off
	v_lshl_add_u64 v[156:157], s[36:37], 0, v[134:135]
	s_mov_b32 m0, s6
	s_nop 0
	global_load_lds_dwordx4 v[156:157], off
	s_waitcnt vmcnt(8)
	s_waitcnt lgkmcnt(0)
	s_barrier
	s_setprio 1
	s_waitcnt lgkmcnt(0)
	v_mfma_f32_16x16x32_bf16 v[126:129], v[142:145], v[214:217], v[126:129]
	v_mfma_f32_16x16x32_bf16 v[118:121], v[150:153], v[214:217], v[118:121]
	v_mfma_f32_16x16x32_bf16 v[110:113], v[142:145], v[226:229], v[110:113]
	v_mfma_f32_16x16x32_bf16 v[102:105], v[150:153], v[226:229], v[102:105]
	v_mfma_f32_16x16x32_bf16 v[94:97], v[142:145], v[234:237], v[94:97]
	v_mfma_f32_16x16x32_bf16 v[86:89], v[150:153], v[234:237], v[86:89]
	v_mfma_f32_16x16x32_bf16 v[78:81], v[142:145], v[242:245], v[78:81]
	v_mfma_f32_16x16x32_bf16 v[70:73], v[150:153], v[242:245], v[70:73]
	v_mfma_f32_16x16x32_bf16 v[126:129], v[146:149], v[218:221], v[126:129]
	v_mfma_f32_16x16x32_bf16 v[118:121], v[172:175], v[218:221], v[118:121]
	v_mfma_f32_16x16x32_bf16 v[110:113], v[146:149], v[230:233], v[110:113]
	v_mfma_f32_16x16x32_bf16 v[102:105], v[172:175], v[230:233], v[102:105]
	v_mfma_f32_16x16x32_bf16 v[94:97], v[146:149], v[238:241], v[94:97]
	v_mfma_f32_16x16x32_bf16 v[86:89], v[172:175], v[238:241], v[86:89]
	v_mfma_f32_16x16x32_bf16 v[78:81], v[146:149], v[246:249], v[78:81]
	v_mfma_f32_16x16x32_bf16 v[70:73], v[172:175], v[246:249], v[70:73]
	s_setprio 0
	s_setprio 1
	v_mfma_f32_16x16x32_bf16 v[122:125], v[176:179], v[214:217], v[122:125]
	v_mfma_f32_16x16x32_bf16 v[114:117], v[206:209], v[214:217], v[114:117]
	v_mfma_f32_16x16x32_bf16 v[106:109], v[176:179], v[226:229], v[106:109]
	v_mfma_f32_16x16x32_bf16 v[98:101], v[206:209], v[226:229], v[98:101]
	v_mfma_f32_16x16x32_bf16 v[90:93], v[176:179], v[234:237], v[90:93]
	v_mfma_f32_16x16x32_bf16 v[82:85], v[206:209], v[234:237], v[82:85]
	v_mfma_f32_16x16x32_bf16 v[74:77], v[176:179], v[242:245], v[74:77]
	v_mfma_f32_16x16x32_bf16 v[66:69], v[206:209], v[242:245], v[66:69]
	v_mfma_f32_16x16x32_bf16 v[122:125], v[202:205], v[218:221], v[122:125]
	v_mfma_f32_16x16x32_bf16 v[114:117], v[210:213], v[218:221], v[114:117]
	v_mfma_f32_16x16x32_bf16 v[106:109], v[202:205], v[230:233], v[106:109]
	v_mfma_f32_16x16x32_bf16 v[98:101], v[210:213], v[230:233], v[98:101]
	v_mfma_f32_16x16x32_bf16 v[90:93], v[202:205], v[238:241], v[90:93]
	v_mfma_f32_16x16x32_bf16 v[82:85], v[210:213], v[238:241], v[82:85]
	v_mfma_f32_16x16x32_bf16 v[74:77], v[202:205], v[246:249], v[74:77]
	v_mfma_f32_16x16x32_bf16 v[66:69], v[210:213], v[246:249], v[66:69]
	s_setprio 0
	s_barrier
	s_add_i32 s36, s41, s68
	v_lshl_add_u64 v[156:157], v[180:181], 0, s[94:95]
	s_mov_b32 m0, s36
	ds_read_b128 v[214:217], v200 offset:49152
	ds_read_b128 v[218:221], v200 offset:50176
	ds_read_b128 v[226:229], v200 offset:51200
	ds_read_b128 v[230:233], v200 offset:52224
	ds_read_b128 v[234:237], v200 offset:53248
	ds_read_b128 v[238:241], v200 offset:54272
	ds_read_b128 v[242:245], v200 offset:55296
	ds_read_b128 v[246:249], v200 offset:56320
	global_load_lds_dwordx4 v[156:157], off
	s_add_i32 m0, s36, 0x2000
	s_add_u32 s4, s4, 0x80080
	v_lshl_add_u64 v[156:157], v[222:223], 0, s[94:95]
	s_addc_u32 s5, s5, 0
	s_add_i32 s36, s42, s68
	global_load_lds_dwordx4 v[156:157], off
	v_lshl_add_u64 v[156:157], s[4:5], 0, v[132:133]
	s_mov_b32 m0, s36
	v_lshl_add_u64 v[154:155], v[154:155], 0, s[94:95]
	global_load_lds_dwordx4 v[156:157], off
	v_lshl_add_u64 v[156:157], s[4:5], 0, v[136:137]
	s_add_i32 m0, s36, 0x2000
	s_nop 0
	global_load_lds_dwordx4 v[156:157], off
	v_lshl_add_u64 v[156:157], v[250:251], 0, s[94:95]
	s_mov_b32 m0, s7
	s_nop 0
	global_load_lds_dwordx4 v[156:157], off
	s_mov_b32 m0, s60
	s_nop 0
	global_load_lds_dwordx4 v[154:155], off
	s_waitcnt vmcnt(8)
	s_waitcnt lgkmcnt(0)
	s_barrier
	s_setprio 1
	s_waitcnt lgkmcnt(0)
	v_mfma_f32_16x16x32_bf16 v[62:65], v[142:145], v[214:217], v[62:65]
	v_mfma_f32_16x16x32_bf16 v[54:57], v[150:153], v[214:217], v[54:57]
	v_mfma_f32_16x16x32_bf16 v[46:49], v[142:145], v[226:229], v[46:49]
	v_mfma_f32_16x16x32_bf16 v[38:41], v[150:153], v[226:229], v[38:41]
	v_mfma_f32_16x16x32_bf16 v[30:33], v[142:145], v[234:237], v[30:33]
	v_mfma_f32_16x16x32_bf16 v[22:25], v[150:153], v[234:237], v[22:25]
	v_mfma_f32_16x16x32_bf16 v[14:17], v[142:145], v[242:245], v[14:17]
	v_mfma_f32_16x16x32_bf16 v[4:7], v[150:153], v[242:245], v[4:7]
	v_mfma_f32_16x16x32_bf16 v[62:65], v[146:149], v[218:221], v[62:65]
	v_mfma_f32_16x16x32_bf16 v[54:57], v[172:175], v[218:221], v[54:57]
	v_mfma_f32_16x16x32_bf16 v[46:49], v[146:149], v[230:233], v[46:49]
	v_mfma_f32_16x16x32_bf16 v[38:41], v[172:175], v[230:233], v[38:41]
	v_mfma_f32_16x16x32_bf16 v[30:33], v[146:149], v[238:241], v[30:33]
	v_mfma_f32_16x16x32_bf16 v[22:25], v[172:175], v[238:241], v[22:25]
	v_mfma_f32_16x16x32_bf16 v[14:17], v[146:149], v[246:249], v[14:17]
	v_mfma_f32_16x16x32_bf16 v[4:7], v[172:175], v[246:249], v[4:7]
	s_setprio 0
	s_setprio 1
	v_mfma_f32_16x16x32_bf16 v[58:61], v[176:179], v[214:217], v[58:61]
	v_mfma_f32_16x16x32_bf16 v[50:53], v[206:209], v[214:217], v[50:53]
	v_mfma_f32_16x16x32_bf16 v[42:45], v[176:179], v[226:229], v[42:45]
	v_mfma_f32_16x16x32_bf16 v[34:37], v[206:209], v[226:229], v[34:37]
	v_mfma_f32_16x16x32_bf16 v[26:29], v[176:179], v[234:237], v[26:29]
	v_mfma_f32_16x16x32_bf16 v[18:21], v[206:209], v[234:237], v[18:21]
	v_mfma_f32_16x16x32_bf16 v[10:13], v[176:179], v[242:245], v[10:13]
	v_mfma_f32_16x16x32_bf16 v[0:3], v[206:209], v[242:245], v[0:3]
	v_mfma_f32_16x16x32_bf16 v[58:61], v[202:205], v[218:221], v[58:61]
	v_mfma_f32_16x16x32_bf16 v[50:53], v[210:213], v[218:221], v[50:53]
	v_mfma_f32_16x16x32_bf16 v[42:45], v[202:205], v[230:233], v[42:45]
	v_mfma_f32_16x16x32_bf16 v[34:37], v[210:213], v[230:233], v[34:37]
	v_mfma_f32_16x16x32_bf16 v[26:29], v[202:205], v[238:241], v[26:29]
	v_mfma_f32_16x16x32_bf16 v[18:21], v[210:213], v[238:241], v[18:21]
	v_mfma_f32_16x16x32_bf16 v[10:13], v[202:205], v[246:249], v[10:13]
	v_mfma_f32_16x16x32_bf16 v[0:3], v[210:213], v[246:249], v[0:3]
	s_setprio 0
	s_barrier
	s_add_i32 s40, s40, 2
	s_add_u32 s23, s23, 0x100
	s_addc_u32 s31, s31, 0
	s_add_u32 s34, s34, 0x100
	s_addc_u32 s35, s35, 0
	s_cmp_gt_u32 s40, 29

.LBB0_723:
	s_ashr_i32 s35, s34, 31
	s_lshl_b64 s[16:17], s[34:35], 20
	s_add_u32 s52, s14, s16
	s_addc_u32 s53, s15, s17
	s_and_b64 s[16:17], s[40:41], exec
	s_cselect_b32 s16, s53, s37
	s_cselect_b32 s17, s52, s36
	s_ashr_i32 s31, s30, 31
	s_lshl_b64 s[56:57], s[30:31], 20
	s_add_u32 s56, s46, s56
	s_addc_u32 s57, s47, s57
	s_and_b64 s[60:61], s[40:41], exec
	s_cselect_b32 s31, s57, s5
	s_cselect_b32 s35, s56, s4
	s_add_u32 s43, s4, 0x100
	s_addc_u32 s59, s5, 0
	s_add_u32 s36, s36, 0x80080
	v_mov_b32_e32 v0, 0
	s_addc_u32 s37, s37, 0
	s_mov_b32 s68, -2
	s_waitcnt lgkmcnt(0)
	s_add_u32 s4, s36, 0xfff80080
	s_addc_u32 s5, s37, -1
	s_add_i32 s48, 0, 0x10000
	s_cmp_eq_u32 s68, 28
	s_cselect_b32 s61, s16, s5
	s_cselect_b32 s60, s17, s4
	v_add_u32_e32 v8, s48, v171
	s_cselect_b32 s5, s31, s59
	s_cselect_b32 s4, s35, s43
	s_add_i32 s49, 0, 0x14000
	ds_read_b128 v[140:143], v8
	ds_read_b128 v[144:147], v8 offset:1024
	ds_read_b128 v[148:151], v8 offset:2048
	ds_read_b128 v[172:175], v8 offset:3072
	v_add_u32_e32 v8, s49, v171
	ds_read_b128 v[176:179], v8
	ds_read_b128 v[194:197], v8 offset:1024
	ds_read_b128 v[198:201], v8 offset:2048
	ds_read_b128 v[202:205], v8 offset:3072
	v_lshl_add_u64 v[152:153], s[36:37], 0, v[138:139]
	s_add_i32 m0, s7, 0xc000
	ds_read_b128 v[206:209], v193
	ds_read_b128 v[210:213], v193 offset:1024
	ds_read_b128 v[214:217], v193 offset:2048
	ds_read_b128 v[218:221], v193 offset:3072
	ds_read_b128 v[226:229], v193 offset:4096
	ds_read_b128 v[230:233], v193 offset:5120
	ds_read_b128 v[234:237], v193 offset:6144
	ds_read_b128 v[238:241], v193 offset:7168
	global_load_lds_dwordx4 v[152:153], off
	v_lshl_add_u64 v[152:153], s[36:37], 0, v[136:137]
	s_add_i32 m0, s7, 0xe000
	s_nop 0
	global_load_lds_dwordx4 v[152:153], off
	s_waitcnt vmcnt(8)
	s_waitcnt lgkmcnt(0)
	s_barrier
	s_setprio 1
	s_waitcnt lgkmcnt(0)
	v_mfma_f32_16x16x32_bf16 v[126:129], v[140:143], v[206:209], 0
	v_mfma_f32_16x16x32_bf16 v[122:125], v[148:151], v[206:209], 0
	v_mfma_f32_16x16x32_bf16 v[110:113], v[140:143], v[214:217], 0
	v_mfma_f32_16x16x32_bf16 v[106:109], v[148:151], v[214:217], 0
	v_mfma_f32_16x16x32_bf16 v[94:97], v[140:143], v[226:229], 0
	v_mfma_f32_16x16x32_bf16 v[90:93], v[148:151], v[226:229], 0
	v_mfma_f32_16x16x32_bf16 v[78:81], v[140:143], v[234:237], 0
	v_mfma_f32_16x16x32_bf16 v[74:77], v[148:151], v[234:237], 0
	v_mfma_f32_16x16x32_bf16 v[126:129], v[144:147], v[210:213], v[126:129]
	v_mfma_f32_16x16x32_bf16 v[122:125], v[172:175], v[210:213], v[122:125]
	v_mfma_f32_16x16x32_bf16 v[110:113], v[144:147], v[218:221], v[110:113]
	v_mfma_f32_16x16x32_bf16 v[106:109], v[172:175], v[218:221], v[106:109]
	v_mfma_f32_16x16x32_bf16 v[94:97], v[144:147], v[230:233], v[94:97]
	v_mfma_f32_16x16x32_bf16 v[90:93], v[172:175], v[230:233], v[90:93]
	v_mfma_f32_16x16x32_bf16 v[78:81], v[144:147], v[238:241], v[78:81]
	v_mfma_f32_16x16x32_bf16 v[74:77], v[172:175], v[238:241], v[74:77]
	s_setprio 0
	s_setprio 1
	v_mfma_f32_16x16x32_bf16 v[118:121], v[176:179], v[206:209], 0
	v_mfma_f32_16x16x32_bf16 v[114:117], v[198:201], v[206:209], 0
	v_mfma_f32_16x16x32_bf16 v[102:105], v[176:179], v[214:217], 0
	v_mfma_f32_16x16x32_bf16 v[98:101], v[198:201], v[214:217], 0
	v_mfma_f32_16x16x32_bf16 v[86:89], v[176:179], v[226:229], 0
	v_mfma_f32_16x16x32_bf16 v[82:85], v[198:201], v[226:229], 0
	v_mfma_f32_16x16x32_bf16 v[70:73], v[176:179], v[234:237], 0
	v_mfma_f32_16x16x32_bf16 v[66:69], v[198:201], v[234:237], 0
	v_mfma_f32_16x16x32_bf16 v[118:121], v[194:197], v[210:213], v[118:121]
	v_mfma_f32_16x16x32_bf16 v[114:117], v[202:205], v[210:213], v[114:117]
	v_mfma_f32_16x16x32_bf16 v[102:105], v[194:197], v[218:221], v[102:105]
	v_mfma_f32_16x16x32_bf16 v[98:101], v[202:205], v[218:221], v[98:101]
	v_mfma_f32_16x16x32_bf16 v[86:89], v[194:197], v[230:233], v[86:89]
	v_mfma_f32_16x16x32_bf16 v[82:85], v[202:205], v[230:233], v[82:85]
	v_mfma_f32_16x16x32_bf16 v[70:73], v[194:197], v[238:241], v[70:73]
	v_mfma_f32_16x16x32_bf16 v[66:69], v[202:205], v[238:241], v[66:69]
	s_setprio 0
	s_barrier
	s_add_i32 s48, s48, s6
	v_lshl_add_u64 v[152:153], s[4:5], 0, v[130:131]
	s_mov_b32 m0, s48
	ds_read_b128 v[206:209], v193 offset:16384
	ds_read_b128 v[210:213], v193 offset:17408
	ds_read_b128 v[214:217], v193 offset:18432
	ds_read_b128 v[218:221], v193 offset:19456
	ds_read_b128 v[226:229], v193 offset:20480
	ds_read_b128 v[230:233], v193 offset:21504
	ds_read_b128 v[234:237], v193 offset:22528
	ds_read_b128 v[238:241], v193 offset:23552
	global_load_lds_dwordx4 v[152:153], off
	s_add_i32 m0, s48, 0x2000
	s_add_u32 vcc_lo, s4, 0x80000
	v_lshl_add_u64 v[222:223], s[4:5], 0, v[132:133]
	s_addc_u32 vcc_hi, s5, 0
	s_add_i32 s48, s49, s6
	global_load_lds_dwordx4 v[222:223], off
	v_lshl_add_u64 v[242:243], vcc, 0, v[130:131]
	s_mov_b32 m0, s48
	v_lshl_add_u64 v[244:245], s[60:61], 0, v[132:133]
	global_load_lds_dwordx4 v[242:243], off
	v_lshl_add_u64 v[242:243], vcc, 0, v[132:133]
	s_add_i32 m0, s48, 0x2000
	s_nop 0
	global_load_lds_dwordx4 v[242:243], off
	v_lshl_add_u64 v[242:243], s[60:61], 0, v[130:131]
	s_mov_b32 m0, s7
	s_nop 0
	global_load_lds_dwordx4 v[242:243], off
	s_mov_b32 m0, s8
	s_nop 0
	global_load_lds_dwordx4 v[244:245], off
	s_waitcnt vmcnt(8)
	s_waitcnt lgkmcnt(0)
	s_barrier
	s_setprio 1
	s_waitcnt lgkmcnt(0)
	v_mfma_f32_16x16x32_bf16 v[62:65], v[140:143], v[206:209], 0
	v_mfma_f32_16x16x32_bf16 v[58:61], v[148:151], v[206:209], 0
	v_mfma_f32_16x16x32_bf16 v[46:49], v[140:143], v[214:217], 0
	v_mfma_f32_16x16x32_bf16 v[42:45], v[148:151], v[214:217], 0
	v_mfma_f32_16x16x32_bf16 v[30:33], v[140:143], v[226:229], 0
	v_mfma_f32_16x16x32_bf16 v[26:29], v[148:151], v[226:229], 0
	v_mfma_f32_16x16x32_bf16 v[14:17], v[140:143], v[234:237], 0
	v_mfma_f32_16x16x32_bf16 v[10:13], v[148:151], v[234:237], 0
	v_mfma_f32_16x16x32_bf16 v[62:65], v[144:147], v[210:213], v[62:65]
	v_mfma_f32_16x16x32_bf16 v[58:61], v[172:175], v[210:213], v[58:61]
	v_mfma_f32_16x16x32_bf16 v[46:49], v[144:147], v[218:221], v[46:49]
	v_mfma_f32_16x16x32_bf16 v[42:45], v[172:175], v[218:221], v[42:45]
	v_mfma_f32_16x16x32_bf16 v[30:33], v[144:147], v[230:233], v[30:33]
	v_mfma_f32_16x16x32_bf16 v[26:29], v[172:175], v[230:233], v[26:29]
	v_mfma_f32_16x16x32_bf16 v[14:17], v[144:147], v[238:241], v[14:17]
	v_mfma_f32_16x16x32_bf16 v[10:13], v[172:175], v[238:241], v[10:13]
	s_setprio 0
	s_setprio 1
	v_mfma_f32_16x16x32_bf16 v[54:57], v[176:179], v[206:209], 0
	v_mfma_f32_16x16x32_bf16 v[50:53], v[198:201], v[206:209], 0
	v_mfma_f32_16x16x32_bf16 v[38:41], v[176:179], v[214:217], 0
	v_mfma_f32_16x16x32_bf16 v[34:37], v[198:201], v[214:217], 0
	v_mfma_f32_16x16x32_bf16 v[22:25], v[176:179], v[226:229], 0
	v_mfma_f32_16x16x32_bf16 v[18:21], v[198:201], v[226:229], 0
	v_mfma_f32_16x16x32_bf16 v[4:7], v[176:179], v[234:237], 0
	v_mfma_f32_16x16x32_bf16 v[0:3], v[198:201], v[234:237], 0
	v_mfma_f32_16x16x32_bf16 v[54:57], v[194:197], v[210:213], v[54:57]
	v_mfma_f32_16x16x32_bf16 v[50:53], v[202:205], v[210:213], v[50:53]
	v_mfma_f32_16x16x32_bf16 v[38:41], v[194:197], v[218:221], v[38:41]
	v_mfma_f32_16x16x32_bf16 v[34:37], v[202:205], v[218:221], v[34:37]
	v_mfma_f32_16x16x32_bf16 v[22:25], v[194:197], v[230:233], v[22:25]
	v_mfma_f32_16x16x32_bf16 v[18:21], v[202:205], v[230:233], v[18:21]
	v_mfma_f32_16x16x32_bf16 v[4:7], v[194:197], v[238:241], v[4:7]
	v_mfma_f32_16x16x32_bf16 v[0:3], v[202:205], v[238:241], v[0:3]
	s_setprio 0
	s_barrier
	s_add_i32 s48, 0, 0x18000
	v_add_u32_e32 v8, s48, v171
	s_add_i32 s49, 0, 0x1c000
	ds_read_b128 v[140:143], v8
	ds_read_b128 v[144:147], v8 offset:1024
	ds_read_b128 v[148:151], v8 offset:2048
	ds_read_b128 v[172:175], v8 offset:3072
	v_add_u32_e32 v8, s49, v171
	ds_read_b128 v[176:179], v8
	ds_read_b128 v[194:197], v8 offset:1024
	ds_read_b128 v[198:201], v8 offset:2048
	ds_read_b128 v[202:205], v8 offset:3072
	s_add_u32 s60, s60, 0x80000
	s_addc_u32 s61, s61, 0
	s_mov_b32 m0, s9
	v_lshl_add_u64 v[246:247], s[60:61], 0, v[130:131]
	ds_read_b128 v[206:209], v193 offset:32768
	ds_read_b128 v[210:213], v193 offset:33792
	ds_read_b128 v[214:217], v193 offset:34816
	ds_read_b128 v[218:221], v193 offset:35840
	ds_read_b128 v[226:229], v193 offset:36864
	ds_read_b128 v[230:233], v193 offset:37888
	ds_read_b128 v[234:237], v193 offset:38912
	ds_read_b128 v[238:241], v193 offset:39936
	global_load_lds_dwordx4 v[246:247], off
	v_lshl_add_u64 v[246:247], s[60:61], 0, v[132:133]
	s_mov_b32 m0, s62
	s_nop 0
	global_load_lds_dwordx4 v[246:247], off
	s_waitcnt vmcnt(8)
	s_waitcnt lgkmcnt(0)
	s_barrier
	s_setprio 1
	s_waitcnt lgkmcnt(0)
	v_mfma_f32_16x16x32_bf16 v[126:129], v[140:143], v[206:209], v[126:129]
	v_mfma_f32_16x16x32_bf16 v[122:125], v[148:151], v[206:209], v[122:125]
	v_mfma_f32_16x16x32_bf16 v[110:113], v[140:143], v[214:217], v[110:113]
	v_mfma_f32_16x16x32_bf16 v[106:109], v[148:151], v[214:217], v[106:109]
	v_mfma_f32_16x16x32_bf16 v[94:97], v[140:143], v[226:229], v[94:97]
	v_mfma_f32_16x16x32_bf16 v[90:93], v[148:151], v[226:229], v[90:93]
	v_mfma_f32_16x16x32_bf16 v[78:81], v[140:143], v[234:237], v[78:81]
	v_mfma_f32_16x16x32_bf16 v[74:77], v[148:151], v[234:237], v[74:77]
	v_mfma_f32_16x16x32_bf16 v[126:129], v[144:147], v[210:213], v[126:129]
	v_mfma_f32_16x16x32_bf16 v[122:125], v[172:175], v[210:213], v[122:125]
	v_mfma_f32_16x16x32_bf16 v[110:113], v[144:147], v[218:221], v[110:113]
	v_mfma_f32_16x16x32_bf16 v[106:109], v[172:175], v[218:221], v[106:109]
	v_mfma_f32_16x16x32_bf16 v[94:97], v[144:147], v[230:233], v[94:97]
	v_mfma_f32_16x16x32_bf16 v[90:93], v[172:175], v[230:233], v[90:93]
	v_mfma_f32_16x16x32_bf16 v[78:81], v[144:147], v[238:241], v[78:81]
	v_mfma_f32_16x16x32_bf16 v[74:77], v[172:175], v[238:241], v[74:77]
	s_setprio 0
	s_setprio 1
	v_mfma_f32_16x16x32_bf16 v[118:121], v[176:179], v[206:209], v[118:121]
	v_mfma_f32_16x16x32_bf16 v[114:117], v[198:201], v[206:209], v[114:117]
	v_mfma_f32_16x16x32_bf16 v[102:105], v[176:179], v[214:217], v[102:105]
	v_mfma_f32_16x16x32_bf16 v[98:101], v[198:201], v[214:217], v[98:101]
	v_mfma_f32_16x16x32_bf16 v[86:89], v[176:179], v[226:229], v[86:89]
	v_mfma_f32_16x16x32_bf16 v[82:85], v[198:201], v[226:229], v[82:85]
	v_mfma_f32_16x16x32_bf16 v[70:73], v[176:179], v[234:237], v[70:73]
	v_mfma_f32_16x16x32_bf16 v[66:69], v[198:201], v[234:237], v[66:69]
	v_mfma_f32_16x16x32_bf16 v[118:121], v[194:197], v[210:213], v[118:121]
	v_mfma_f32_16x16x32_bf16 v[114:117], v[202:205], v[210:213], v[114:117]
	v_mfma_f32_16x16x32_bf16 v[102:105], v[194:197], v[218:221], v[102:105]
	v_mfma_f32_16x16x32_bf16 v[98:101], v[202:205], v[218:221], v[98:101]
	v_mfma_f32_16x16x32_bf16 v[86:89], v[194:197], v[230:233], v[86:89]
	v_mfma_f32_16x16x32_bf16 v[82:85], v[202:205], v[230:233], v[82:85]
	v_mfma_f32_16x16x32_bf16 v[70:73], v[194:197], v[238:241], v[70:73]
	v_mfma_f32_16x16x32_bf16 v[66:69], v[202:205], v[238:241], v[66:69]
	s_setprio 0
	s_barrier
	s_add_i32 s48, s48, s6
	v_lshl_add_u64 v[152:153], v[152:153], 0, s[94:95]
	s_mov_b32 m0, s48
	ds_read_b128 v[206:209], v193 offset:49152
	ds_read_b128 v[210:213], v193 offset:50176
	ds_read_b128 v[214:217], v193 offset:51200
	ds_read_b128 v[218:221], v193 offset:52224
	ds_read_b128 v[226:229], v193 offset:53248
	ds_read_b128 v[230:233], v193 offset:54272
	ds_read_b128 v[234:237], v193 offset:55296
	ds_read_b128 v[238:241], v193 offset:56320
	global_load_lds_dwordx4 v[152:153], off
	s_add_i32 m0, s48, 0x2000
	s_add_u32 s4, s4, 0x80080
	v_lshl_add_u64 v[152:153], v[222:223], 0, s[94:95]
	s_addc_u32 s5, s5, 0
	s_add_i32 s48, s49, s6
	global_load_lds_dwordx4 v[152:153], off
	v_lshl_add_u64 v[152:153], s[4:5], 0, v[130:131]
	s_mov_b32 m0, s48
	s_nop 0
	global_load_lds_dwordx4 v[152:153], off
	v_lshl_add_u64 v[152:153], s[4:5], 0, v[132:133]
	s_add_i32 m0, s48, 0x2000
	s_nop 0
	global_load_lds_dwordx4 v[152:153], off
	v_lshl_add_u64 v[152:153], v[242:243], 0, s[94:95]
	s_mov_b32 m0, s86
	s_nop 0
	global_load_lds_dwordx4 v[152:153], off
	v_lshl_add_u64 v[152:153], v[244:245], 0, s[94:95]
	s_mov_b32 m0, s88
	s_nop 0
	global_load_lds_dwordx4 v[152:153], off
	s_waitcnt vmcnt(8)
	s_waitcnt lgkmcnt(0)
	s_barrier
	s_setprio 1
	s_waitcnt lgkmcnt(0)
	v_mfma_f32_16x16x32_bf16 v[62:65], v[140:143], v[206:209], v[62:65]
	v_mfma_f32_16x16x32_bf16 v[58:61], v[148:151], v[206:209], v[58:61]
	v_mfma_f32_16x16x32_bf16 v[46:49], v[140:143], v[214:217], v[46:49]
	v_mfma_f32_16x16x32_bf16 v[42:45], v[148:151], v[214:217], v[42:45]
	v_mfma_f32_16x16x32_bf16 v[30:33], v[140:143], v[226:229], v[30:33]
	v_mfma_f32_16x16x32_bf16 v[26:29], v[148:151], v[226:229], v[26:29]
	v_mfma_f32_16x16x32_bf16 v[14:17], v[140:143], v[234:237], v[14:17]
	v_mfma_f32_16x16x32_bf16 v[10:13], v[148:151], v[234:237], v[10:13]
	v_mfma_f32_16x16x32_bf16 v[62:65], v[144:147], v[210:213], v[62:65]
	v_mfma_f32_16x16x32_bf16 v[58:61], v[172:175], v[210:213], v[58:61]
	v_mfma_f32_16x16x32_bf16 v[46:49], v[144:147], v[218:221], v[46:49]
	v_mfma_f32_16x16x32_bf16 v[42:45], v[172:175], v[218:221], v[42:45]
	v_mfma_f32_16x16x32_bf16 v[30:33], v[144:147], v[230:233], v[30:33]
	v_mfma_f32_16x16x32_bf16 v[26:29], v[172:175], v[230:233], v[26:29]
	v_mfma_f32_16x16x32_bf16 v[14:17], v[144:147], v[238:241], v[14:17]
	v_mfma_f32_16x16x32_bf16 v[10:13], v[172:175], v[238:241], v[10:13]
	s_setprio 0
	s_setprio 1
	v_mfma_f32_16x16x32_bf16 v[54:57], v[176:179], v[206:209], v[54:57]
	v_mfma_f32_16x16x32_bf16 v[50:53], v[198:201], v[206:209], v[50:53]
	v_mfma_f32_16x16x32_bf16 v[38:41], v[176:179], v[214:217], v[38:41]
	v_mfma_f32_16x16x32_bf16 v[34:37], v[198:201], v[214:217], v[34:37]
	v_mfma_f32_16x16x32_bf16 v[22:25], v[176:179], v[226:229], v[22:25]
	v_mfma_f32_16x16x32_bf16 v[18:21], v[198:201], v[226:229], v[18:21]
	v_mfma_f32_16x16x32_bf16 v[4:7], v[176:179], v[234:237], v[4:7]
	v_mfma_f32_16x16x32_bf16 v[0:3], v[198:201], v[234:237], v[0:3]
	v_mfma_f32_16x16x32_bf16 v[54:57], v[194:197], v[210:213], v[54:57]
	v_mfma_f32_16x16x32_bf16 v[50:53], v[202:205], v[210:213], v[50:53]
	v_mfma_f32_16x16x32_bf16 v[38:41], v[194:197], v[218:221], v[38:41]
	v_mfma_f32_16x16x32_bf16 v[34:37], v[202:205], v[218:221], v[34:37]
	v_mfma_f32_16x16x32_bf16 v[22:25], v[194:197], v[230:233], v[22:25]
	v_mfma_f32_16x16x32_bf16 v[18:21], v[202:205], v[230:233], v[18:21]
	v_mfma_f32_16x16x32_bf16 v[4:7], v[194:197], v[238:241], v[4:7]
	v_mfma_f32_16x16x32_bf16 v[0:3], v[202:205], v[238:241], v[0:3]
	s_setprio 0
	s_barrier
	s_add_i32 s68, s68, 2
	s_add_u32 s43, s43, 0x100
	s_addc_u32 s59, s59, 0
	s_add_u32 s36, s36, 0x100
	s_addc_u32 s37, s37, 0
	s_cmp_gt_u32 s68, 29

.LBB0_825:
	s_add_u32 s85, s4, 0x100
	s_addc_u32 s88, s5, 0
	s_add_u32 s36, s36, 0x80
	v_mov_b32_e32 v0, 0
	s_addc_u32 s37, s37, 0
	s_mov_b32 s4, 0
	s_waitcnt lgkmcnt(0)
	s_add_i32 s91, s4, 2
	s_add_u32 vcc_lo, s36, 0x80
	s_addc_u32 s5, s37, 0
	s_add_i32 s48, 0, 0x10000
	s_cmp_eq_u32 s59, s4
	s_cselect_b32 s5, s43, s5
	s_cselect_b32 s4, s42, vcc_lo
	v_add_u32_e32 v152, s48, v172
	s_cselect_b32 vcc_hi, s53, s88
	s_cselect_b32 vcc_lo, s52, s85
	s_add_i32 s49, 0, 0x14000
	ds_read_b128 v[126:129], v152
	ds_read_b128 v[134:137], v152 offset:1024
	ds_read_b128 v[148:151], v152 offset:2048
	ds_read_b128 v[176:179], v152 offset:3072
	v_add_u32_e32 v152, s49, v172
	ds_read_b128 v[190:193], v152
	ds_read_b128 v[194:197], v152 offset:1024
	ds_read_b128 v[198:201], v152 offset:2048
	ds_read_b128 v[202:205], v152 offset:3072
	v_lshl_add_u64 v[152:153], s[36:37], 0, v[146:147]
	s_add_i32 m0, s8, 0xc000
	ds_read_b128 v[206:209], v174
	ds_read_b128 v[210:213], v174 offset:1024
	ds_read_b128 v[214:217], v174 offset:2048
	ds_read_b128 v[218:221], v174 offset:3072
	ds_read_b128 v[226:229], v174 offset:4096
	ds_read_b128 v[230:233], v174 offset:5120
	ds_read_b128 v[234:237], v174 offset:6144
	ds_read_b128 v[238:241], v174 offset:7168
	global_load_lds_dwordx4 v[152:153], off
	v_lshl_add_u64 v[152:153], s[36:37], 0, v[144:145]
	s_add_i32 m0, s8, 0xe000
	s_nop 0
	global_load_lds_dwordx4 v[152:153], off
	s_waitcnt vmcnt(8)
	s_waitcnt lgkmcnt(0)
	s_barrier
	s_setprio 1
	s_waitcnt lgkmcnt(0)
	v_mfma_f32_16x16x32_bf16 v[130:133], v[126:129], v[206:209], 0
	v_mfma_f32_16x16x32_bf16 v[122:125], v[148:151], v[206:209], 0
	v_mfma_f32_16x16x32_bf16 v[110:113], v[126:129], v[214:217], 0
	v_mfma_f32_16x16x32_bf16 v[106:109], v[148:151], v[214:217], 0
	v_mfma_f32_16x16x32_bf16 v[94:97], v[126:129], v[226:229], 0
	v_mfma_f32_16x16x32_bf16 v[90:93], v[148:151], v[226:229], 0
	v_mfma_f32_16x16x32_bf16 v[78:81], v[126:129], v[234:237], 0
	v_mfma_f32_16x16x32_bf16 v[74:77], v[148:151], v[234:237], 0
	v_mfma_f32_16x16x32_bf16 v[130:133], v[134:137], v[210:213], v[130:133]
	v_mfma_f32_16x16x32_bf16 v[122:125], v[176:179], v[210:213], v[122:125]
	v_mfma_f32_16x16x32_bf16 v[110:113], v[134:137], v[218:221], v[110:113]
	v_mfma_f32_16x16x32_bf16 v[106:109], v[176:179], v[218:221], v[106:109]
	v_mfma_f32_16x16x32_bf16 v[94:97], v[134:137], v[230:233], v[94:97]
	v_mfma_f32_16x16x32_bf16 v[90:93], v[176:179], v[230:233], v[90:93]
	v_mfma_f32_16x16x32_bf16 v[78:81], v[134:137], v[238:241], v[78:81]
	v_mfma_f32_16x16x32_bf16 v[74:77], v[176:179], v[238:241], v[74:77]
	s_setprio 0
	s_setprio 1
	v_mfma_f32_16x16x32_bf16 v[118:121], v[190:193], v[206:209], 0
	v_mfma_f32_16x16x32_bf16 v[114:117], v[198:201], v[206:209], 0
	v_mfma_f32_16x16x32_bf16 v[102:105], v[190:193], v[214:217], 0
	v_mfma_f32_16x16x32_bf16 v[98:101], v[198:201], v[214:217], 0
	v_mfma_f32_16x16x32_bf16 v[86:89], v[190:193], v[226:229], 0
	v_mfma_f32_16x16x32_bf16 v[82:85], v[198:201], v[226:229], 0
	v_mfma_f32_16x16x32_bf16 v[70:73], v[190:193], v[234:237], 0
	v_mfma_f32_16x16x32_bf16 v[66:69], v[198:201], v[234:237], 0
	v_mfma_f32_16x16x32_bf16 v[118:121], v[194:197], v[210:213], v[118:121]
	v_mfma_f32_16x16x32_bf16 v[114:117], v[202:205], v[210:213], v[114:117]
	v_mfma_f32_16x16x32_bf16 v[102:105], v[194:197], v[218:221], v[102:105]
	v_mfma_f32_16x16x32_bf16 v[98:101], v[202:205], v[218:221], v[98:101]
	v_mfma_f32_16x16x32_bf16 v[86:89], v[194:197], v[230:233], v[86:89]
	v_mfma_f32_16x16x32_bf16 v[82:85], v[202:205], v[230:233], v[82:85]
	v_mfma_f32_16x16x32_bf16 v[70:73], v[194:197], v[238:241], v[70:73]
	v_mfma_f32_16x16x32_bf16 v[66:69], v[202:205], v[238:241], v[66:69]
	s_setprio 0
	s_barrier
	s_add_i32 s48, s48, s7
	v_lshl_add_u64 v[152:153], vcc, 0, v[8:9]
	s_mov_b32 m0, s48
	ds_read_b128 v[206:209], v174 offset:16384
	ds_read_b128 v[210:213], v174 offset:17408
	ds_read_b128 v[214:217], v174 offset:18432
	ds_read_b128 v[218:221], v174 offset:19456
	ds_read_b128 v[226:229], v174 offset:20480
	ds_read_b128 v[230:233], v174 offset:21504
	ds_read_b128 v[234:237], v174 offset:22528
	ds_read_b128 v[238:241], v174 offset:23552
	global_load_lds_dwordx4 v[152:153], off
	s_add_i32 m0, s48, 0x2000
	v_lshl_add_u64 v[180:181], vcc, 0, v[142:143]
	s_add_u32 vcc_lo, vcc_lo, s68
	s_addc_u32 vcc_hi, vcc_hi, 0
	s_add_i32 s48, s49, s7
	global_load_lds_dwordx4 v[180:181], off
	v_lshl_add_u64 v[222:223], vcc, 0, v[8:9]
	s_mov_b32 m0, s48
	v_lshl_add_u64 v[242:243], vcc, 0, v[142:143]
	global_load_lds_dwordx4 v[222:223], off
	s_add_i32 m0, s48, 0x2000
	v_lshl_add_u64 v[244:245], s[4:5], 0, v[138:139]
	global_load_lds_dwordx4 v[242:243], off
	s_mov_b32 m0, s8
	v_lshl_add_u64 v[246:247], s[4:5], 0, v[140:141]
	global_load_lds_dwordx4 v[244:245], off
	s_mov_b32 m0, s9
	s_nop 0
	global_load_lds_dwordx4 v[246:247], off
	s_waitcnt vmcnt(8)
	s_waitcnt lgkmcnt(0)
	s_barrier
	s_setprio 1
	s_waitcnt lgkmcnt(0)
	v_mfma_f32_16x16x32_bf16 v[62:65], v[126:129], v[206:209], 0
	v_mfma_f32_16x16x32_bf16 v[58:61], v[148:151], v[206:209], 0
	v_mfma_f32_16x16x32_bf16 v[46:49], v[126:129], v[214:217], 0
	v_mfma_f32_16x16x32_bf16 v[42:45], v[148:151], v[214:217], 0
	v_mfma_f32_16x16x32_bf16 v[30:33], v[126:129], v[226:229], 0
	v_mfma_f32_16x16x32_bf16 v[26:29], v[148:151], v[226:229], 0
	v_mfma_f32_16x16x32_bf16 v[14:17], v[126:129], v[234:237], 0
	v_mfma_f32_16x16x32_bf16 v[10:13], v[148:151], v[234:237], 0
	v_mfma_f32_16x16x32_bf16 v[62:65], v[134:137], v[210:213], v[62:65]
	v_mfma_f32_16x16x32_bf16 v[58:61], v[176:179], v[210:213], v[58:61]
	v_mfma_f32_16x16x32_bf16 v[46:49], v[134:137], v[218:221], v[46:49]
	v_mfma_f32_16x16x32_bf16 v[42:45], v[176:179], v[218:221], v[42:45]
	v_mfma_f32_16x16x32_bf16 v[30:33], v[134:137], v[230:233], v[30:33]
	v_mfma_f32_16x16x32_bf16 v[26:29], v[176:179], v[230:233], v[26:29]
	v_mfma_f32_16x16x32_bf16 v[14:17], v[134:137], v[238:241], v[14:17]
	v_mfma_f32_16x16x32_bf16 v[10:13], v[176:179], v[238:241], v[10:13]
	s_setprio 0
	s_setprio 1
	v_mfma_f32_16x16x32_bf16 v[54:57], v[190:193], v[206:209], 0
	v_mfma_f32_16x16x32_bf16 v[50:53], v[198:201], v[206:209], 0
	v_mfma_f32_16x16x32_bf16 v[38:41], v[190:193], v[214:217], 0
	v_mfma_f32_16x16x32_bf16 v[34:37], v[198:201], v[214:217], 0
	v_mfma_f32_16x16x32_bf16 v[22:25], v[190:193], v[226:229], 0
	v_mfma_f32_16x16x32_bf16 v[18:21], v[198:201], v[226:229], 0
	v_mfma_f32_16x16x32_bf16 v[4:7], v[190:193], v[234:237], 0
	v_mfma_f32_16x16x32_bf16 v[0:3], v[198:201], v[234:237], 0
	v_mfma_f32_16x16x32_bf16 v[54:57], v[194:197], v[210:213], v[54:57]
	v_mfma_f32_16x16x32_bf16 v[50:53], v[202:205], v[210:213], v[50:53]
	v_mfma_f32_16x16x32_bf16 v[38:41], v[194:197], v[218:221], v[38:41]
	v_mfma_f32_16x16x32_bf16 v[34:37], v[202:205], v[218:221], v[34:37]
	v_mfma_f32_16x16x32_bf16 v[22:25], v[194:197], v[230:233], v[22:25]
	v_mfma_f32_16x16x32_bf16 v[18:21], v[202:205], v[230:233], v[18:21]
	v_mfma_f32_16x16x32_bf16 v[4:7], v[194:197], v[238:241], v[4:7]
	v_mfma_f32_16x16x32_bf16 v[0:3], v[202:205], v[238:241], v[0:3]
	s_setprio 0
	s_barrier
	s_add_i32 s48, 0, 0x18000
	v_add_u32_e32 v154, s48, v172
	s_add_i32 s49, 0, 0x1c000
	ds_read_b128 v[126:129], v154
	ds_read_b128 v[134:137], v154 offset:1024
	ds_read_b128 v[148:151], v154 offset:2048
	ds_read_b128 v[176:179], v154 offset:3072
	v_add_u32_e32 v154, s49, v172
	ds_read_b128 v[190:193], v154
	ds_read_b128 v[194:197], v154 offset:1024
	ds_read_b128 v[198:201], v154 offset:2048
	ds_read_b128 v[202:205], v154 offset:3072
	s_add_u32 s4, s4, s68
	s_addc_u32 s5, s5, 0
	s_mov_b32 m0, s54
	v_lshl_add_u64 v[248:249], s[4:5], 0, v[138:139]
	ds_read_b128 v[206:209], v174 offset:32768
	ds_read_b128 v[210:213], v174 offset:33792
	ds_read_b128 v[214:217], v174 offset:34816
	ds_read_b128 v[218:221], v174 offset:35840
	ds_read_b128 v[226:229], v174 offset:36864
	ds_read_b128 v[230:233], v174 offset:37888
	ds_read_b128 v[234:237], v174 offset:38912
	ds_read_b128 v[238:241], v174 offset:39936
	global_load_lds_dwordx4 v[248:249], off
	v_lshl_add_u64 v[248:249], s[4:5], 0, v[140:141]
	s_mov_b32 m0, s55
	s_nop 0
	global_load_lds_dwordx4 v[248:249], off
	s_waitcnt vmcnt(8)
	s_waitcnt lgkmcnt(0)
	s_barrier
	s_setprio 1
	s_waitcnt lgkmcnt(0)
	v_mfma_f32_16x16x32_bf16 v[130:133], v[126:129], v[206:209], v[130:133]
	v_mfma_f32_16x16x32_bf16 v[122:125], v[148:151], v[206:209], v[122:125]
	v_mfma_f32_16x16x32_bf16 v[110:113], v[126:129], v[214:217], v[110:113]
	v_mfma_f32_16x16x32_bf16 v[106:109], v[148:151], v[214:217], v[106:109]
	v_mfma_f32_16x16x32_bf16 v[94:97], v[126:129], v[226:229], v[94:97]
	v_mfma_f32_16x16x32_bf16 v[90:93], v[148:151], v[226:229], v[90:93]
	v_mfma_f32_16x16x32_bf16 v[78:81], v[126:129], v[234:237], v[78:81]
	v_mfma_f32_16x16x32_bf16 v[74:77], v[148:151], v[234:237], v[74:77]
	v_mfma_f32_16x16x32_bf16 v[130:133], v[134:137], v[210:213], v[130:133]
	v_mfma_f32_16x16x32_bf16 v[122:125], v[176:179], v[210:213], v[122:125]
	v_mfma_f32_16x16x32_bf16 v[110:113], v[134:137], v[218:221], v[110:113]
	v_mfma_f32_16x16x32_bf16 v[106:109], v[176:179], v[218:221], v[106:109]
	v_mfma_f32_16x16x32_bf16 v[94:97], v[134:137], v[230:233], v[94:97]
	v_mfma_f32_16x16x32_bf16 v[90:93], v[176:179], v[230:233], v[90:93]
	v_mfma_f32_16x16x32_bf16 v[78:81], v[134:137], v[238:241], v[78:81]
	v_mfma_f32_16x16x32_bf16 v[74:77], v[176:179], v[238:241], v[74:77]
	s_setprio 0
	s_setprio 1
	v_mfma_f32_16x16x32_bf16 v[118:121], v[190:193], v[206:209], v[118:121]
	v_mfma_f32_16x16x32_bf16 v[114:117], v[198:201], v[206:209], v[114:117]
	v_mfma_f32_16x16x32_bf16 v[102:105], v[190:193], v[214:217], v[102:105]
	v_mfma_f32_16x16x32_bf16 v[98:101], v[198:201], v[214:217], v[98:101]
	v_mfma_f32_16x16x32_bf16 v[86:89], v[190:193], v[226:229], v[86:89]
	v_mfma_f32_16x16x32_bf16 v[82:85], v[198:201], v[226:229], v[82:85]
	v_mfma_f32_16x16x32_bf16 v[70:73], v[190:193], v[234:237], v[70:73]
	v_mfma_f32_16x16x32_bf16 v[66:69], v[198:201], v[234:237], v[66:69]
	v_mfma_f32_16x16x32_bf16 v[118:121], v[194:197], v[210:213], v[118:121]
	v_mfma_f32_16x16x32_bf16 v[114:117], v[202:205], v[210:213], v[114:117]
	v_mfma_f32_16x16x32_bf16 v[102:105], v[194:197], v[218:221], v[102:105]
	v_mfma_f32_16x16x32_bf16 v[98:101], v[202:205], v[218:221], v[98:101]
	v_mfma_f32_16x16x32_bf16 v[86:89], v[194:197], v[230:233], v[86:89]
	v_mfma_f32_16x16x32_bf16 v[82:85], v[202:205], v[230:233], v[82:85]
	v_mfma_f32_16x16x32_bf16 v[70:73], v[194:197], v[238:241], v[70:73]
	v_mfma_f32_16x16x32_bf16 v[66:69], v[202:205], v[238:241], v[66:69]
	s_setprio 0
	s_barrier
	s_add_i32 s4, s48, s7
	v_lshl_add_u64 v[152:153], v[152:153], 0, s[94:95]
	s_mov_b32 m0, s4
	ds_read_b128 v[206:209], v174 offset:49152
	ds_read_b128 v[210:213], v174 offset:50176
	ds_read_b128 v[214:217], v174 offset:51200
	ds_read_b128 v[218:221], v174 offset:52224
	ds_read_b128 v[226:229], v174 offset:53248
	ds_read_b128 v[230:233], v174 offset:54272
	ds_read_b128 v[234:237], v174 offset:55296
	ds_read_b128 v[238:241], v174 offset:56320
	global_load_lds_dwordx4 v[152:153], off
	v_lshl_add_u64 v[152:153], v[180:181], 0, s[94:95]
	s_add_i32 m0, s4, 0x2000
	s_add_i32 s4, s49, s7
	global_load_lds_dwordx4 v[152:153], off
	v_lshl_add_u64 v[152:153], v[222:223], 0, s[94:95]
	s_mov_b32 m0, s4
	s_nop 0
	global_load_lds_dwordx4 v[152:153], off
	v_lshl_add_u64 v[152:153], v[242:243], 0, s[94:95]
	s_add_i32 m0, s4, 0x2000
	s_nop 0
	global_load_lds_dwordx4 v[152:153], off
	v_lshl_add_u64 v[152:153], v[244:245], 0, s[94:95]
	s_mov_b32 m0, s57
	s_nop 0
	global_load_lds_dwordx4 v[152:153], off
	v_lshl_add_u64 v[152:153], v[246:247], 0, s[94:95]
	s_mov_b32 m0, s58
	s_nop 0
	global_load_lds_dwordx4 v[152:153], off
	s_waitcnt vmcnt(8)
	s_waitcnt lgkmcnt(0)
	s_barrier
	s_setprio 1
	s_waitcnt lgkmcnt(0)
	v_mfma_f32_16x16x32_bf16 v[62:65], v[126:129], v[206:209], v[62:65]
	v_mfma_f32_16x16x32_bf16 v[58:61], v[148:151], v[206:209], v[58:61]
	v_mfma_f32_16x16x32_bf16 v[46:49], v[126:129], v[214:217], v[46:49]
	v_mfma_f32_16x16x32_bf16 v[42:45], v[148:151], v[214:217], v[42:45]
	v_mfma_f32_16x16x32_bf16 v[30:33], v[126:129], v[226:229], v[30:33]
	v_mfma_f32_16x16x32_bf16 v[26:29], v[148:151], v[226:229], v[26:29]
	v_mfma_f32_16x16x32_bf16 v[14:17], v[126:129], v[234:237], v[14:17]
	v_mfma_f32_16x16x32_bf16 v[10:13], v[148:151], v[234:237], v[10:13]
	v_mfma_f32_16x16x32_bf16 v[62:65], v[134:137], v[210:213], v[62:65]
	v_mfma_f32_16x16x32_bf16 v[58:61], v[176:179], v[210:213], v[58:61]
	v_mfma_f32_16x16x32_bf16 v[46:49], v[134:137], v[218:221], v[46:49]
	v_mfma_f32_16x16x32_bf16 v[42:45], v[176:179], v[218:221], v[42:45]
	v_mfma_f32_16x16x32_bf16 v[30:33], v[134:137], v[230:233], v[30:33]
	v_mfma_f32_16x16x32_bf16 v[26:29], v[176:179], v[230:233], v[26:29]
	v_mfma_f32_16x16x32_bf16 v[14:17], v[134:137], v[238:241], v[14:17]
	v_mfma_f32_16x16x32_bf16 v[10:13], v[176:179], v[238:241], v[10:13]
	s_setprio 0
	s_setprio 1
	v_mfma_f32_16x16x32_bf16 v[54:57], v[190:193], v[206:209], v[54:57]
	v_mfma_f32_16x16x32_bf16 v[50:53], v[198:201], v[206:209], v[50:53]
	v_mfma_f32_16x16x32_bf16 v[38:41], v[190:193], v[214:217], v[38:41]
	v_mfma_f32_16x16x32_bf16 v[34:37], v[198:201], v[214:217], v[34:37]
	v_mfma_f32_16x16x32_bf16 v[22:25], v[190:193], v[226:229], v[22:25]
	v_mfma_f32_16x16x32_bf16 v[18:21], v[198:201], v[226:229], v[18:21]
	v_mfma_f32_16x16x32_bf16 v[4:7], v[190:193], v[234:237], v[4:7]
	v_mfma_f32_16x16x32_bf16 v[0:3], v[198:201], v[234:237], v[0:3]
	v_mfma_f32_16x16x32_bf16 v[54:57], v[194:197], v[210:213], v[54:57]
	v_mfma_f32_16x16x32_bf16 v[50:53], v[202:205], v[210:213], v[50:53]
	v_mfma_f32_16x16x32_bf16 v[38:41], v[194:197], v[218:221], v[38:41]
	v_mfma_f32_16x16x32_bf16 v[34:37], v[202:205], v[218:221], v[34:37]
	v_mfma_f32_16x16x32_bf16 v[22:25], v[194:197], v[230:233], v[22:25]
	v_mfma_f32_16x16x32_bf16 v[18:21], v[202:205], v[230:233], v[18:21]
	v_mfma_f32_16x16x32_bf16 v[4:7], v[194:197], v[238:241], v[4:7]
	v_mfma_f32_16x16x32_bf16 v[0:3], v[202:205], v[238:241], v[0:3]
	s_setprio 0
	s_barrier
	s_add_u32 s85, s85, 0x100
	s_addc_u32 s88, s88, 0
	s_add_u32 s36, s36, 0x100
	s_addc_u32 s37, s37, 0
	s_cmp_ge_u32 s91, s56
	s_mov_b32 s4, s91

.LBB0_942:
	s_ashr_i32 s27, s26, 31
	s_lshl_b64 s[28:29], s[26:27], 20
	s_add_u32 s28, s14, s28
	s_addc_u32 s29, s15, s29
	s_and_b64 s[30:31], s[38:39], exec
	s_cselect_b32 s17, s29, s37
	s_cselect_b32 s27, s28, s36
	s_ashr_i32 s25, s24, 31
	s_lshl_b64 s[30:31], s[24:25], 20
	s_add_u32 s30, s6, s30
	s_addc_u32 s31, s7, s31
	s_and_b64 s[40:41], s[38:39], exec
	s_cselect_b32 s25, s31, s5
	s_cselect_b32 s49, s30, s4
	s_add_u32 s50, s4, 0x100
	s_addc_u32 s51, s5, 0
	s_add_u32 s36, s36, 0x80080
	v_mov_b32_e32 v0, 0
	s_addc_u32 s37, s37, 0
	s_mov_b32 s52, -2
	s_add_u32 s4, s36, 0xfff80080
	s_addc_u32 s5, s37, -1
	s_add_i32 s53, 0, 0x10000
	s_cmp_eq_u32 s52, 28
	s_cselect_b32 s41, s17, s5
	s_cselect_b32 s40, s27, s4
	v_add_u32_e32 v8, s53, v178
	s_cselect_b32 s5, s25, s51
	s_cselect_b32 s4, s49, s50
	s_add_i32 s56, 0, 0x14000
	ds_read_b128 v[142:145], v8
	ds_read_b128 v[146:149], v8 offset:1024
	ds_read_b128 v[150:153], v8 offset:2048
	ds_read_b128 v[172:175], v8 offset:3072
	v_add_u32_e32 v8, s56, v178
	ds_read_b128 v[190:193], v8
	ds_read_b128 v[194:197], v8 offset:1024
	ds_read_b128 v[198:201], v8 offset:2048
	ds_read_b128 v[202:205], v8 offset:3072
	v_lshl_add_u64 v[176:177], s[36:37], 0, v[140:141]
	s_add_i32 m0, s35, 0xc000
	ds_read_b128 v[206:209], v180
	ds_read_b128 v[210:213], v180 offset:1024
	ds_read_b128 v[214:217], v180 offset:2048
	ds_read_b128 v[218:221], v180 offset:3072
	ds_read_b128 v[226:229], v180 offset:4096
	ds_read_b128 v[230:233], v180 offset:5120
	ds_read_b128 v[234:237], v180 offset:6144
	ds_read_b128 v[238:241], v180 offset:7168
	global_load_lds_dwordx4 v[176:177], off
	v_lshl_add_u64 v[176:177], s[36:37], 0, v[138:139]
	s_add_i32 m0, s35, 0xe000
	s_nop 0
	global_load_lds_dwordx4 v[176:177], off
	s_waitcnt vmcnt(8)
	s_waitcnt lgkmcnt(0)
	s_barrier
	s_setprio 1
	s_waitcnt lgkmcnt(0)
	v_mfma_f32_16x16x32_bf16 v[126:129], v[142:145], v[206:209], 0
	v_mfma_f32_16x16x32_bf16 v[118:121], v[150:153], v[206:209], 0
	v_mfma_f32_16x16x32_bf16 v[106:109], v[142:145], v[214:217], 0
	v_mfma_f32_16x16x32_bf16 v[98:101], v[150:153], v[214:217], 0
	v_mfma_f32_16x16x32_bf16 v[90:93], v[142:145], v[226:229], 0
	v_mfma_f32_16x16x32_bf16 v[82:85], v[150:153], v[226:229], 0
	v_mfma_f32_16x16x32_bf16 v[74:77], v[142:145], v[234:237], 0
	v_mfma_f32_16x16x32_bf16 v[66:69], v[150:153], v[234:237], 0
	v_mfma_f32_16x16x32_bf16 v[126:129], v[146:149], v[210:213], v[126:129]
	v_mfma_f32_16x16x32_bf16 v[118:121], v[172:175], v[210:213], v[118:121]
	v_mfma_f32_16x16x32_bf16 v[106:109], v[146:149], v[218:221], v[106:109]
	v_mfma_f32_16x16x32_bf16 v[98:101], v[172:175], v[218:221], v[98:101]
	v_mfma_f32_16x16x32_bf16 v[90:93], v[146:149], v[230:233], v[90:93]
	v_mfma_f32_16x16x32_bf16 v[82:85], v[172:175], v[230:233], v[82:85]
	v_mfma_f32_16x16x32_bf16 v[74:77], v[146:149], v[238:241], v[74:77]
	v_mfma_f32_16x16x32_bf16 v[66:69], v[172:175], v[238:241], v[66:69]
	s_setprio 0
	s_setprio 1
	v_mfma_f32_16x16x32_bf16 v[122:125], v[190:193], v[206:209], 0
	v_mfma_f32_16x16x32_bf16 v[114:117], v[198:201], v[206:209], 0
	v_mfma_f32_16x16x32_bf16 v[110:113], v[190:193], v[214:217], 0
	v_mfma_f32_16x16x32_bf16 v[102:105], v[198:201], v[214:217], 0
	v_mfma_f32_16x16x32_bf16 v[94:97], v[190:193], v[226:229], 0
	v_mfma_f32_16x16x32_bf16 v[86:89], v[198:201], v[226:229], 0
	v_mfma_f32_16x16x32_bf16 v[78:81], v[190:193], v[234:237], 0
	v_mfma_f32_16x16x32_bf16 v[70:73], v[198:201], v[234:237], 0
	v_mfma_f32_16x16x32_bf16 v[122:125], v[194:197], v[210:213], v[122:125]
	v_mfma_f32_16x16x32_bf16 v[114:117], v[202:205], v[210:213], v[114:117]
	v_mfma_f32_16x16x32_bf16 v[110:113], v[194:197], v[218:221], v[110:113]
	v_mfma_f32_16x16x32_bf16 v[102:105], v[202:205], v[218:221], v[102:105]
	v_mfma_f32_16x16x32_bf16 v[94:97], v[194:197], v[230:233], v[94:97]
	v_mfma_f32_16x16x32_bf16 v[86:89], v[202:205], v[230:233], v[86:89]
	v_mfma_f32_16x16x32_bf16 v[78:81], v[194:197], v[238:241], v[78:81]
	v_mfma_f32_16x16x32_bf16 v[70:73], v[202:205], v[238:241], v[70:73]
	s_setprio 0
	s_barrier
	s_add_i32 s53, s53, s8
	v_lshl_add_u64 v[176:177], s[4:5], 0, v[134:135]
	s_mov_b32 m0, s53
	ds_read_b128 v[206:209], v180 offset:16384
	ds_read_b128 v[210:213], v180 offset:17408
	ds_read_b128 v[214:217], v180 offset:18432
	ds_read_b128 v[218:221], v180 offset:19456
	ds_read_b128 v[226:229], v180 offset:20480
	ds_read_b128 v[230:233], v180 offset:21504
	ds_read_b128 v[234:237], v180 offset:22528
	ds_read_b128 v[238:241], v180 offset:23552
	global_load_lds_dwordx4 v[176:177], off
	s_add_i32 m0, s53, 0x2000
	s_add_u32 s54, s4, 0x80000
	v_lshl_add_u64 v[222:223], s[4:5], 0, v[130:131]
	s_addc_u32 s55, s5, 0
	s_add_i32 s53, s56, s8
	global_load_lds_dwordx4 v[222:223], off
	v_lshl_add_u64 v[242:243], s[54:55], 0, v[134:135]
	s_mov_b32 m0, s53
	v_lshl_add_u64 v[244:245], s[40:41], 0, v[132:133]
	global_load_lds_dwordx4 v[242:243], off
	v_lshl_add_u64 v[242:243], s[54:55], 0, v[130:131]
	s_add_i32 m0, s53, 0x2000
	s_nop 0
	global_load_lds_dwordx4 v[242:243], off
	v_lshl_add_u64 v[242:243], s[40:41], 0, v[136:137]
	s_mov_b32 m0, s35
	s_nop 0
	global_load_lds_dwordx4 v[242:243], off
	s_mov_b32 m0, s42
	s_nop 0
	global_load_lds_dwordx4 v[244:245], off
	s_waitcnt vmcnt(8)
	s_waitcnt lgkmcnt(0)
	s_barrier
	s_setprio 1
	s_waitcnt lgkmcnt(0)
	v_mfma_f32_16x16x32_bf16 v[58:61], v[142:145], v[206:209], 0
	v_mfma_f32_16x16x32_bf16 v[50:53], v[150:153], v[206:209], 0
	v_mfma_f32_16x16x32_bf16 v[42:45], v[142:145], v[214:217], 0
	v_mfma_f32_16x16x32_bf16 v[34:37], v[150:153], v[214:217], 0
	v_mfma_f32_16x16x32_bf16 v[26:29], v[142:145], v[226:229], 0
	v_mfma_f32_16x16x32_bf16 v[18:21], v[150:153], v[226:229], 0
	v_mfma_f32_16x16x32_bf16 v[10:13], v[142:145], v[234:237], 0
	v_mfma_f32_16x16x32_bf16 v[4:7], v[150:153], v[234:237], 0
	v_mfma_f32_16x16x32_bf16 v[58:61], v[146:149], v[210:213], v[58:61]
	v_mfma_f32_16x16x32_bf16 v[50:53], v[172:175], v[210:213], v[50:53]
	v_mfma_f32_16x16x32_bf16 v[42:45], v[146:149], v[218:221], v[42:45]
	v_mfma_f32_16x16x32_bf16 v[34:37], v[172:175], v[218:221], v[34:37]
	v_mfma_f32_16x16x32_bf16 v[26:29], v[146:149], v[230:233], v[26:29]
	v_mfma_f32_16x16x32_bf16 v[18:21], v[172:175], v[230:233], v[18:21]
	v_mfma_f32_16x16x32_bf16 v[10:13], v[146:149], v[238:241], v[10:13]
	v_mfma_f32_16x16x32_bf16 v[4:7], v[172:175], v[238:241], v[4:7]
	s_setprio 0
	s_setprio 1
	v_mfma_f32_16x16x32_bf16 v[62:65], v[190:193], v[206:209], 0
	v_mfma_f32_16x16x32_bf16 v[54:57], v[198:201], v[206:209], 0
	v_mfma_f32_16x16x32_bf16 v[46:49], v[190:193], v[214:217], 0
	v_mfma_f32_16x16x32_bf16 v[38:41], v[198:201], v[214:217], 0
	v_mfma_f32_16x16x32_bf16 v[30:33], v[190:193], v[226:229], 0
	v_mfma_f32_16x16x32_bf16 v[22:25], v[198:201], v[226:229], 0
	v_mfma_f32_16x16x32_bf16 v[14:17], v[190:193], v[234:237], 0
	v_mfma_f32_16x16x32_bf16 v[0:3], v[198:201], v[234:237], 0
	v_mfma_f32_16x16x32_bf16 v[62:65], v[194:197], v[210:213], v[62:65]
	v_mfma_f32_16x16x32_bf16 v[54:57], v[202:205], v[210:213], v[54:57]
	v_mfma_f32_16x16x32_bf16 v[46:49], v[194:197], v[218:221], v[46:49]
	v_mfma_f32_16x16x32_bf16 v[38:41], v[202:205], v[218:221], v[38:41]
	v_mfma_f32_16x16x32_bf16 v[30:33], v[194:197], v[230:233], v[30:33]
	v_mfma_f32_16x16x32_bf16 v[22:25], v[202:205], v[230:233], v[22:25]
	v_mfma_f32_16x16x32_bf16 v[14:17], v[194:197], v[238:241], v[14:17]
	v_mfma_f32_16x16x32_bf16 v[0:3], v[202:205], v[238:241], v[0:3]
	s_setprio 0
	s_barrier
	s_add_i32 s53, 0, 0x18000
	v_add_u32_e32 v8, s53, v178
	s_add_i32 s54, 0, 0x1c000
	ds_read_b128 v[142:145], v8
	ds_read_b128 v[146:149], v8 offset:1024
	ds_read_b128 v[150:153], v8 offset:2048
	ds_read_b128 v[172:175], v8 offset:3072
	v_add_u32_e32 v8, s54, v178
	ds_read_b128 v[190:193], v8
	ds_read_b128 v[194:197], v8 offset:1024
	ds_read_b128 v[198:201], v8 offset:2048
	ds_read_b128 v[202:205], v8 offset:3072
	s_add_u32 s40, s40, 0x80000
	s_addc_u32 s41, s41, 0
	s_mov_b32 m0, s43
	v_lshl_add_u64 v[246:247], s[40:41], 0, v[136:137]
	ds_read_b128 v[206:209], v180 offset:32768
	ds_read_b128 v[210:213], v180 offset:33792
	ds_read_b128 v[214:217], v180 offset:34816
	ds_read_b128 v[218:221], v180 offset:35840
	ds_read_b128 v[226:229], v180 offset:36864
	ds_read_b128 v[230:233], v180 offset:37888
	ds_read_b128 v[234:237], v180 offset:38912
	ds_read_b128 v[238:241], v180 offset:39936
	global_load_lds_dwordx4 v[246:247], off
	v_lshl_add_u64 v[246:247], s[40:41], 0, v[132:133]
	s_mov_b32 m0, s44
	s_nop 0
	global_load_lds_dwordx4 v[246:247], off
	s_waitcnt vmcnt(8)
	s_waitcnt lgkmcnt(0)
	s_barrier
	s_setprio 1
	s_waitcnt lgkmcnt(0)
	v_mfma_f32_16x16x32_bf16 v[126:129], v[142:145], v[206:209], v[126:129]
	v_mfma_f32_16x16x32_bf16 v[118:121], v[150:153], v[206:209], v[118:121]
	v_mfma_f32_16x16x32_bf16 v[106:109], v[142:145], v[214:217], v[106:109]
	v_mfma_f32_16x16x32_bf16 v[98:101], v[150:153], v[214:217], v[98:101]
	v_mfma_f32_16x16x32_bf16 v[90:93], v[142:145], v[226:229], v[90:93]
	v_mfma_f32_16x16x32_bf16 v[82:85], v[150:153], v[226:229], v[82:85]
	v_mfma_f32_16x16x32_bf16 v[74:77], v[142:145], v[234:237], v[74:77]
	v_mfma_f32_16x16x32_bf16 v[66:69], v[150:153], v[234:237], v[66:69]
	v_mfma_f32_16x16x32_bf16 v[126:129], v[146:149], v[210:213], v[126:129]
	v_mfma_f32_16x16x32_bf16 v[118:121], v[172:175], v[210:213], v[118:121]
	v_mfma_f32_16x16x32_bf16 v[106:109], v[146:149], v[218:221], v[106:109]
	v_mfma_f32_16x16x32_bf16 v[98:101], v[172:175], v[218:221], v[98:101]
	v_mfma_f32_16x16x32_bf16 v[90:93], v[146:149], v[230:233], v[90:93]
	v_mfma_f32_16x16x32_bf16 v[82:85], v[172:175], v[230:233], v[82:85]
	v_mfma_f32_16x16x32_bf16 v[74:77], v[146:149], v[238:241], v[74:77]
	v_mfma_f32_16x16x32_bf16 v[66:69], v[172:175], v[238:241], v[66:69]
	s_setprio 0
	s_setprio 1
	v_mfma_f32_16x16x32_bf16 v[122:125], v[190:193], v[206:209], v[122:125]
	v_mfma_f32_16x16x32_bf16 v[114:117], v[198:201], v[206:209], v[114:117]
	v_mfma_f32_16x16x32_bf16 v[110:113], v[190:193], v[214:217], v[110:113]
	v_mfma_f32_16x16x32_bf16 v[102:105], v[198:201], v[214:217], v[102:105]
	v_mfma_f32_16x16x32_bf16 v[94:97], v[190:193], v[226:229], v[94:97]
	v_mfma_f32_16x16x32_bf16 v[86:89], v[198:201], v[226:229], v[86:89]
	v_mfma_f32_16x16x32_bf16 v[78:81], v[190:193], v[234:237], v[78:81]
	v_mfma_f32_16x16x32_bf16 v[70:73], v[198:201], v[234:237], v[70:73]
	v_mfma_f32_16x16x32_bf16 v[122:125], v[194:197], v[210:213], v[122:125]
	v_mfma_f32_16x16x32_bf16 v[114:117], v[202:205], v[210:213], v[114:117]
	v_mfma_f32_16x16x32_bf16 v[110:113], v[194:197], v[218:221], v[110:113]
	v_mfma_f32_16x16x32_bf16 v[102:105], v[202:205], v[218:221], v[102:105]
	v_mfma_f32_16x16x32_bf16 v[94:97], v[194:197], v[230:233], v[94:97]
	v_mfma_f32_16x16x32_bf16 v[86:89], v[202:205], v[230:233], v[86:89]
	v_mfma_f32_16x16x32_bf16 v[78:81], v[194:197], v[238:241], v[78:81]
	v_mfma_f32_16x16x32_bf16 v[70:73], v[202:205], v[238:241], v[70:73]
	s_setprio 0
	s_barrier
	s_add_i32 s40, s53, s8
	v_lshl_add_u64 v[176:177], v[176:177], 0, s[94:95]
	s_mov_b32 m0, s40
	ds_read_b128 v[206:209], v180 offset:49152
	ds_read_b128 v[210:213], v180 offset:50176
	ds_read_b128 v[214:217], v180 offset:51200
	ds_read_b128 v[218:221], v180 offset:52224
	ds_read_b128 v[226:229], v180 offset:53248
	ds_read_b128 v[230:233], v180 offset:54272
	ds_read_b128 v[234:237], v180 offset:55296
	ds_read_b128 v[238:241], v180 offset:56320
	global_load_lds_dwordx4 v[176:177], off
	s_add_i32 m0, s40, 0x2000
	s_add_u32 s4, s4, 0x80080
	v_lshl_add_u64 v[176:177], v[222:223], 0, s[94:95]
	s_addc_u32 s5, s5, 0
	s_add_i32 s40, s54, s8
	global_load_lds_dwordx4 v[176:177], off
	v_lshl_add_u64 v[176:177], s[4:5], 0, v[134:135]
	s_mov_b32 m0, s40
	s_nop 0
	global_load_lds_dwordx4 v[176:177], off
	v_lshl_add_u64 v[176:177], s[4:5], 0, v[130:131]
	s_add_i32 m0, s40, 0x2000
	s_nop 0
	global_load_lds_dwordx4 v[176:177], off
	v_lshl_add_u64 v[176:177], v[242:243], 0, s[94:95]
	s_mov_b32 m0, s45
	s_nop 0
	global_load_lds_dwordx4 v[176:177], off
	v_lshl_add_u64 v[176:177], v[244:245], 0, s[94:95]
	s_mov_b32 m0, s46
	s_nop 0
	global_load_lds_dwordx4 v[176:177], off
	s_waitcnt vmcnt(8)
	s_waitcnt lgkmcnt(0)
	s_barrier
	s_setprio 1
	s_waitcnt lgkmcnt(0)
	v_mfma_f32_16x16x32_bf16 v[58:61], v[142:145], v[206:209], v[58:61]
	v_mfma_f32_16x16x32_bf16 v[50:53], v[150:153], v[206:209], v[50:53]
	v_mfma_f32_16x16x32_bf16 v[42:45], v[142:145], v[214:217], v[42:45]
	v_mfma_f32_16x16x32_bf16 v[34:37], v[150:153], v[214:217], v[34:37]
	v_mfma_f32_16x16x32_bf16 v[26:29], v[142:145], v[226:229], v[26:29]
	v_mfma_f32_16x16x32_bf16 v[18:21], v[150:153], v[226:229], v[18:21]
	v_mfma_f32_16x16x32_bf16 v[10:13], v[142:145], v[234:237], v[10:13]
	v_mfma_f32_16x16x32_bf16 v[4:7], v[150:153], v[234:237], v[4:7]
	v_mfma_f32_16x16x32_bf16 v[58:61], v[146:149], v[210:213], v[58:61]
	v_mfma_f32_16x16x32_bf16 v[50:53], v[172:175], v[210:213], v[50:53]
	v_mfma_f32_16x16x32_bf16 v[42:45], v[146:149], v[218:221], v[42:45]
	v_mfma_f32_16x16x32_bf16 v[34:37], v[172:175], v[218:221], v[34:37]
	v_mfma_f32_16x16x32_bf16 v[26:29], v[146:149], v[230:233], v[26:29]
	v_mfma_f32_16x16x32_bf16 v[18:21], v[172:175], v[230:233], v[18:21]
	v_mfma_f32_16x16x32_bf16 v[10:13], v[146:149], v[238:241], v[10:13]
	v_mfma_f32_16x16x32_bf16 v[4:7], v[172:175], v[238:241], v[4:7]
	s_setprio 0
	s_setprio 1
	v_mfma_f32_16x16x32_bf16 v[62:65], v[190:193], v[206:209], v[62:65]
	v_mfma_f32_16x16x32_bf16 v[54:57], v[198:201], v[206:209], v[54:57]
	v_mfma_f32_16x16x32_bf16 v[46:49], v[190:193], v[214:217], v[46:49]
	v_mfma_f32_16x16x32_bf16 v[38:41], v[198:201], v[214:217], v[38:41]
	v_mfma_f32_16x16x32_bf16 v[30:33], v[190:193], v[226:229], v[30:33]
	v_mfma_f32_16x16x32_bf16 v[22:25], v[198:201], v[226:229], v[22:25]
	v_mfma_f32_16x16x32_bf16 v[14:17], v[190:193], v[234:237], v[14:17]
	v_mfma_f32_16x16x32_bf16 v[0:3], v[198:201], v[234:237], v[0:3]
	v_mfma_f32_16x16x32_bf16 v[62:65], v[194:197], v[210:213], v[62:65]
	v_mfma_f32_16x16x32_bf16 v[54:57], v[202:205], v[210:213], v[54:57]
	v_mfma_f32_16x16x32_bf16 v[46:49], v[194:197], v[218:221], v[46:49]
	v_mfma_f32_16x16x32_bf16 v[38:41], v[202:205], v[218:221], v[38:41]
	v_mfma_f32_16x16x32_bf16 v[30:33], v[194:197], v[230:233], v[30:33]
	v_mfma_f32_16x16x32_bf16 v[22:25], v[202:205], v[230:233], v[22:25]
	v_mfma_f32_16x16x32_bf16 v[14:17], v[194:197], v[238:241], v[14:17]
	v_mfma_f32_16x16x32_bf16 v[0:3], v[202:205], v[238:241], v[0:3]
	s_setprio 0
	s_barrier
	s_add_i32 s52, s52, 2
	s_add_u32 s50, s50, 0x100
	s_addc_u32 s51, s51, 0
	s_add_u32 s36, s36, 0x100
	s_addc_u32 s37, s37, 0
	s_cmp_gt_u32 s52, 29
